# speedup vs baseline: 1.0087x; 1.0087x over previous
; #define LAS __attribute__((address_space(3)))
; __device__ __forceinline__ void unpack8(const u32x4 r, float (&v)[8]) { v[0] = bf_lo(r.x); v[1] = bf_hi(r.x); v[2] = bf_lo(r.y); v[3] = bf_hi(r.y); v[4] = bf_lo(r.z); v[5] = bf_hi(r.z); v[6] = bf_lo(r.w); v[7] = bf_hi(r.w); }
; __device__ __forceinline__ u32x4 pack8(const float (&v)[8]) { u32x4 w; w.x = cvt_pk_bf16(v[0], v[1]); w.y = cvt_pk_bf16(v[2], v[3]); w.z = cvt_pk_bf16(v[4], v[5]); w.w = cvt_pk_bf16(v[6], v[7]); return w; }
; __device__ __forceinline__ void norm_store(LAS bf16_t* dst, const u32x4 raw, const float (&g)[8]) {
;     float v[8]; unpack8(raw, v); float ss = 0.f;
; #pragma unroll
;     for (int t = 0; t < 8; ++t) ss += v[t] * v[t];
;     ss += __shfl_xor(ss, 1); ss += __shfl_xor(ss, 2); ss += __shfl_xor(ss, 4);
;     const float rs = __builtin_amdgcn_rsqf(ss * (1.0f / 64.0f) + EPS);
;     float o[8];
; #pragma unroll
;     for (int t = 0; t < 8; ++t) o[t] = v[t] * rs * g[t];
;     *(LAS u32x4*)dst = pack8(o);
; }
; __device__ __forceinline__ void attn_stage(LAS unsigned char* lds, const AttnPre& P, const float (&gq)[8], const float (&gk)[8], int tid) {
;     ...
;     for (int it = 0; it < 2; ++it) norm_store(Qs + (i0 + 64 * it) * AQP + 8 * c, P.q[it], gq);
.LBB0_186:
	v_and_b32_e32 v70, 0xffff0000, v8
	v_lshlrev_b32_e32 v33, 16, v8
	v_mul_f32_e32 v75, v70, v70
	v_lshlrev_b32_e32 v71, 16, v9
	v_fmac_f32_e32 v75, v33, v33
	v_and_b32_e32 v72, 0xffff0000, v9
	v_fmac_f32_e32 v75, v71, v71
	v_lshlrev_b32_e32 v73, 16, v10
	v_fmac_f32_e32 v75, v72, v72
	v_and_b32_e32 v74, 0xffff0000, v10
	v_fmac_f32_e32 v75, v73, v73
	v_and_b32_e32 v34, 0xffff0000, v11
	v_lshlrev_b32_e32 v35, 16, v11
	v_fmac_f32_e32 v75, v74, v74
	v_pk_mul_f32 v[68:69], v[34:35], v[34:35]
	s_nop 0
	v_add_f32_e32 v69, v69, v75
	v_add_f32_e32 v68, v68, v69
	s_nop 1
	v_add_f32_dpp v68, v68, v68 quad_perm:[1,0,3,2] row_mask:0xf bank_mask:0xf
	s_nop 1
	v_add_f32_dpp v68, v68, v68 quad_perm:[2,3,0,1] row_mask:0xf bank_mask:0xf
	s_nop 1
	v_add_f32_dpp v68, v68, v68 row_half_mirror row_mask:0xf bank_mask:0xf
	v_fmamk_f32 v68, v68, 0x3c800000, v204
	v_rsq_f32_e32 v68, v68
	s_nop 0
	v_mul_f32_e32 v69, v68, v70
	v_mul_f32_e32 v70, v68, v71
	v_mul_f32_e32 v33, v68, v33
	v_mul_f32_e32 v69, v137, v69
	v_mul_f32_e32 v70, v138, v70
	v_mul_f32_e32 v71, v68, v72
	v_mul_f32_e32 v72, v68, v73
	v_mul_f32_e32 v73, v68, v74
	v_mul_f32_e32 v33, v136, v33
	v_mul_f32_e32 v71, v139, v71
	v_mul_f32_e32 v72, v140, v72
	v_mul_f32_e32 v73, v141, v73
	v_mul_f32_e32 v35, v68, v35
	v_mul_f32_e32 v34, v68, v34
	v_cvt_pk_bf16_f32 v68, v33, v69
	v_cvt_pk_bf16_f32 v69, v70, v71
	v_cvt_pk_bf16_f32 v70, v72, v73
	v_mul_f32_e32 v35, v142, v35
	v_mul_f32_e32 v34, v143, v34
	v_cvt_pk_bf16_f32 v71, v35, v34
	ds_write_b128 v147, v[68:71]
	v_and_b32_e32 v70, 0xffff0000, v12
	v_lshlrev_b32_e32 v33, 16, v12
	v_mul_f32_e32 v75, v70, v70
	v_lshlrev_b32_e32 v71, 16, v13
	v_fmac_f32_e32 v75, v33, v33
	v_and_b32_e32 v72, 0xffff0000, v13
	v_fmac_f32_e32 v75, v71, v71
	v_lshlrev_b32_e32 v73, 16, v14
	v_fmac_f32_e32 v75, v72, v72
	v_and_b32_e32 v74, 0xffff0000, v14
	v_fmac_f32_e32 v75, v73, v73
	v_and_b32_e32 v34, 0xffff0000, v15
	v_lshlrev_b32_e32 v35, 16, v15
	v_fmac_f32_e32 v75, v74, v74
	v_pk_mul_f32 v[68:69], v[34:35], v[34:35]
	s_nop 0
	v_add_f32_e32 v69, v69, v75
	v_add_f32_e32 v68, v68, v69
	s_nop 1
	v_add_f32_dpp v68, v68, v68 quad_perm:[1,0,3,2] row_mask:0xf bank_mask:0xf
	s_nop 1
	v_add_f32_dpp v68, v68, v68 quad_perm:[2,3,0,1] row_mask:0xf bank_mask:0xf
	s_nop 1
	v_add_f32_dpp v68, v68, v68 row_half_mirror row_mask:0xf bank_mask:0xf
	v_fmamk_f32 v68, v68, 0x3c800000, v204
	v_rsq_f32_e32 v68, v68
	s_nop 0
	v_mul_f32_e32 v69, v68, v70
	v_mul_f32_e32 v70, v68, v71
	v_mul_f32_e32 v71, v68, v72
	v_mul_f32_e32 v33, v68, v33
	v_mul_f32_e32 v69, v137, v69
	v_mul_f32_e32 v70, v138, v70
	v_mul_f32_e32 v71, v139, v71
	v_mul_f32_e32 v72, v68, v73
	v_mul_f32_e32 v73, v68, v74
	v_mul_f32_e32 v35, v68, v35
	v_mul_f32_e32 v34, v68, v34
	v_mul_f32_e32 v33, v136, v33
	v_mul_f32_e32 v72, v140, v72
	v_mul_f32_e32 v73, v141, v73
	v_mul_f32_e32 v35, v142, v35
	v_mul_f32_e32 v34, v143, v34
	v_cvt_pk_bf16_f32 v68, v33, v69
	v_cvt_pk_bf16_f32 v69, v70, v71
	v_cvt_pk_bf16_f32 v70, v72, v73
	v_cvt_pk_bf16_f32 v71, v35, v34
	ds_write_b128 v147, v[68:71] offset:9216
	s_and_saveexec_b64 s[28:29], s[4:5]
	s_cbranch_execnz .LBB0_213
	s_or_b64 exec, exec, s[28:29]
	s_and_saveexec_b64 s[28:29], s[6:7]
	s_cbranch_execnz .LBB0_214

; #define LAS __attribute__((address_space(3)))
; __device__ __forceinline__ void unpack8(const u32x4 r, float (&v)[8]) { v[0] = bf_lo(r.x); v[1] = bf_hi(r.x); v[2] = bf_lo(r.y); v[3] = bf_hi(r.y); v[4] = bf_lo(r.z); v[5] = bf_hi(r.z); v[6] = bf_lo(r.w); v[7] = bf_hi(r.w); }
; __device__ __forceinline__ u32x4 pack8(const float (&v)[8]) { u32x4 w; w.x = cvt_pk_bf16(v[0], v[1]); w.y = cvt_pk_bf16(v[2], v[3]); w.z = cvt_pk_bf16(v[4], v[5]); w.w = cvt_pk_bf16(v[6], v[7]); return w; }
; __device__ __forceinline__ void norm_store(LAS bf16_t* dst, const u32x4 raw, const float (&g)[8]) {
;     float v[8]; unpack8(raw, v); float ss = 0.f;
; #pragma unroll
;     for (int t = 0; t < 8; ++t) ss += v[t] * v[t];
;     ss += __shfl_xor(ss, 1); ss += __shfl_xor(ss, 2); ss += __shfl_xor(ss, 4);
;     const float rs = __builtin_amdgcn_rsqf(ss * (1.0f / 64.0f) + EPS);
;     float o[8];
; #pragma unroll
;     for (int t = 0; t < 8; ++t) o[t] = v[t] * rs * g[t];
;     *(LAS u32x4*)dst = pack8(o);
; }
; __device__ __forceinline__ void attn_stage(LAS unsigned char* lds, const AttnPre& P, const float (&gq)[8], const float (&gk)[8], int tid) {
;     ...
;     for (int it = 0; it < 5; ++it) { const int i = i0 + 64 * it;
;         if (i < ANR) { norm_store(Ks + i * AQP + 8 * c, P.k[it], gk); *(LAS u32x4*)(Vs + i * AQP + 8 * c) = P.v[it]; } }
.LBB0_191:
	v_and_b32_e32 v70, 0xffff0000, v52
	v_lshlrev_b32_e32 v33, 16, v52
	v_mul_f32_e32 v75, v70, v70
	v_lshlrev_b32_e32 v71, 16, v53
	v_fmac_f32_e32 v75, v33, v33
	v_and_b32_e32 v72, 0xffff0000, v53
	v_fmac_f32_e32 v75, v71, v71
	v_lshlrev_b32_e32 v73, 16, v54
	v_fmac_f32_e32 v75, v72, v72
	v_and_b32_e32 v74, 0xffff0000, v54
	v_fmac_f32_e32 v75, v73, v73
	v_and_b32_e32 v34, 0xffff0000, v55
	v_lshlrev_b32_e32 v35, 16, v55
	v_fmac_f32_e32 v75, v74, v74
	v_pk_mul_f32 v[68:69], v[34:35], v[34:35]
	s_nop 0
	v_add_f32_e32 v69, v69, v75
	v_add_f32_e32 v68, v68, v69
	s_nop 1
	v_add_f32_dpp v68, v68, v68 quad_perm:[1,0,3,2] row_mask:0xf bank_mask:0xf
	s_nop 1
	v_add_f32_dpp v68, v68, v68 quad_perm:[2,3,0,1] row_mask:0xf bank_mask:0xf
	s_nop 1
	v_add_f32_dpp v68, v68, v68 row_half_mirror row_mask:0xf bank_mask:0xf
	v_fmamk_f32 v68, v68, 0x3c800000, v204
	v_rsq_f32_e32 v68, v68
	s_nop 0
	v_mul_f32_e32 v69, v68, v70
	v_mul_f32_e32 v70, v68, v71
	v_mul_f32_e32 v71, v68, v72
	v_mul_f32_e32 v33, v68, v33
	v_mul_f32_e32 v72, v68, v73
	v_mul_f32_e32 v69, v5, v69
	v_mul_f32_e32 v70, v6, v70
	v_mul_f32_e32 v71, v7, v71
	v_mul_f32_e32 v73, v68, v74
	v_mul_f32_e32 v35, v68, v35
	v_mul_f32_e32 v34, v68, v34
	v_mul_f32_e32 v33, v4, v33
	v_mul_f32_e32 v72, v0, v72
	v_mul_f32_e32 v73, v1, v73
	v_mul_f32_e32 v35, v2, v35
	v_mul_f32_e32 v34, v3, v34
	v_cvt_pk_bf16_f32 v68, v33, v69
	v_cvt_pk_bf16_f32 v69, v70, v71
	v_cvt_pk_bf16_f32 v70, v72, v73
	v_cvt_pk_bf16_f32 v71, v35, v34
	ds_write_b128 v147, v[68:71] offset:55296
	ds_write_b128 v148, v[56:59] offset:36864

; #define LAS __attribute__((address_space(3)))
; __device__ __forceinline__ void unpack8(const u32x4 r, float (&v)[8]) { v[0] = bf_lo(r.x); v[1] = bf_hi(r.x); v[2] = bf_lo(r.y); v[3] = bf_hi(r.y); v[4] = bf_lo(r.z); v[5] = bf_hi(r.z); v[6] = bf_lo(r.w); v[7] = bf_hi(r.w); }
; __device__ __forceinline__ u32x4 pack8(const float (&v)[8]) { u32x4 w; w.x = cvt_pk_bf16(v[0], v[1]); w.y = cvt_pk_bf16(v[2], v[3]); w.z = cvt_pk_bf16(v[4], v[5]); w.w = cvt_pk_bf16(v[6], v[7]); return w; }
; __device__ __forceinline__ void norm_store(LAS bf16_t* dst, const u32x4 raw, const float (&g)[8]) {
;     float v[8]; unpack8(raw, v); float ss = 0.f;
; #pragma unroll
;     for (int t = 0; t < 8; ++t) ss += v[t] * v[t];
;     ss += __shfl_xor(ss, 1); ss += __shfl_xor(ss, 2); ss += __shfl_xor(ss, 4);
;     const float rs = __builtin_amdgcn_rsqf(ss * (1.0f / 64.0f) + EPS);
;     float o[8];
; #pragma unroll
;     for (int t = 0; t < 8; ++t) o[t] = v[t] * rs * g[t];
;     *(LAS u32x4*)dst = pack8(o);
; }
; __device__ __forceinline__ void attn_stage(LAS unsigned char* lds, const AttnPre& P, const float (&gq)[8], const float (&gk)[8], int tid) {
;     ...
; #pragma unroll
;     for (int it = 0; it < 5; ++it) { const int i = i0 + 64 * it;
;         if (i < ANR) { norm_store(Ks + i * AQP + 8 * c, P.k[it], gk); *(LAS u32x4*)(Vs + i * AQP + 8 * c) = P.v[it]; } }
.LBB0_213:
	v_and_b32_e32 v70, 0xffff0000, v20
	v_lshlrev_b32_e32 v33, 16, v20
	v_mul_f32_e32 v75, v70, v70
	v_lshlrev_b32_e32 v71, 16, v21
	v_fmac_f32_e32 v75, v33, v33
	v_and_b32_e32 v72, 0xffff0000, v21
	v_fmac_f32_e32 v75, v71, v71
	v_lshlrev_b32_e32 v73, 16, v22
	v_fmac_f32_e32 v75, v72, v72
	v_and_b32_e32 v74, 0xffff0000, v22
	v_fmac_f32_e32 v75, v73, v73
	v_and_b32_e32 v34, 0xffff0000, v23
	v_lshlrev_b32_e32 v35, 16, v23
	v_fmac_f32_e32 v75, v74, v74
	v_pk_mul_f32 v[68:69], v[34:35], v[34:35]
	s_nop 0
	v_add_f32_e32 v69, v69, v75
	v_add_f32_e32 v68, v68, v69
	s_nop 1
	v_add_f32_dpp v68, v68, v68 quad_perm:[1,0,3,2] row_mask:0xf bank_mask:0xf
	s_nop 1
	v_add_f32_dpp v68, v68, v68 quad_perm:[2,3,0,1] row_mask:0xf bank_mask:0xf
	s_nop 1
	v_add_f32_dpp v68, v68, v68 row_half_mirror row_mask:0xf bank_mask:0xf
	v_fmamk_f32 v68, v68, 0x3c800000, v204
	v_rsq_f32_e32 v68, v68
	s_nop 0
	v_mul_f32_e32 v69, v68, v70
	v_mul_f32_e32 v70, v68, v71
	v_mul_f32_e32 v71, v68, v72
	v_mul_f32_e32 v33, v68, v33
	v_mul_f32_e32 v72, v68, v73
	v_mul_f32_e32 v69, v5, v69
	v_mul_f32_e32 v70, v6, v70
	v_mul_f32_e32 v71, v7, v71
	v_mul_f32_e32 v73, v68, v74
	v_mul_f32_e32 v35, v68, v35
	v_mul_f32_e32 v34, v68, v34
	v_mul_f32_e32 v33, v4, v33
	v_mul_f32_e32 v72, v0, v72
	v_mul_f32_e32 v73, v1, v73
	v_mul_f32_e32 v35, v2, v35
	v_mul_f32_e32 v34, v3, v34
	v_cvt_pk_bf16_f32 v68, v33, v69
	v_cvt_pk_bf16_f32 v69, v70, v71
	v_cvt_pk_bf16_f32 v70, v72, v73
	v_cvt_pk_bf16_f32 v71, v35, v34
	ds_write_b128 v147, v[68:71] offset:18432
	ds_write_b128 v147, v[24:27] offset:57600
	s_or_b64 exec, exec, s[28:29]
	s_and_saveexec_b64 s[28:29], s[6:7]
	s_cbranch_execz .LBB0_188
.LBB0_214:
	v_and_b32_e32 v70, 0xffff0000, v16
	v_lshlrev_b32_e32 v33, 16, v16
	v_mul_f32_e32 v75, v70, v70
	v_lshlrev_b32_e32 v71, 16, v17
	v_fmac_f32_e32 v75, v33, v33
	v_and_b32_e32 v72, 0xffff0000, v17
	v_fmac_f32_e32 v75, v71, v71
	v_lshlrev_b32_e32 v73, 16, v18
	v_fmac_f32_e32 v75, v72, v72
	v_and_b32_e32 v74, 0xffff0000, v18
	v_fmac_f32_e32 v75, v73, v73
	v_and_b32_e32 v34, 0xffff0000, v19
	v_lshlrev_b32_e32 v35, 16, v19
	v_fmac_f32_e32 v75, v74, v74
	v_pk_mul_f32 v[68:69], v[34:35], v[34:35]
	s_nop 0
	v_add_f32_e32 v69, v69, v75
	v_add_f32_e32 v68, v68, v69
	s_nop 1
	v_add_f32_dpp v68, v68, v68 quad_perm:[1,0,3,2] row_mask:0xf bank_mask:0xf
	s_nop 1
	v_add_f32_dpp v68, v68, v68 quad_perm:[2,3,0,1] row_mask:0xf bank_mask:0xf
	s_nop 1
	v_add_f32_dpp v68, v68, v68 row_half_mirror row_mask:0xf bank_mask:0xf
	v_fmamk_f32 v68, v68, 0x3c800000, v204
	v_rsq_f32_e32 v68, v68
	s_nop 0
	v_mul_f32_e32 v69, v68, v70
	v_mul_f32_e32 v70, v68, v71
	v_mul_f32_e32 v71, v68, v72
	v_mul_f32_e32 v33, v68, v33
	v_mul_f32_e32 v72, v68, v73
	v_mul_f32_e32 v69, v5, v69
	v_mul_f32_e32 v70, v6, v70
	v_mul_f32_e32 v71, v7, v71
	v_mul_f32_e32 v73, v68, v74
	v_mul_f32_e32 v35, v68, v35
	v_mul_f32_e32 v34, v68, v34
	v_mul_f32_e32 v33, v4, v33
	v_mul_f32_e32 v72, v0, v72
	v_mul_f32_e32 v73, v1, v73
	v_mul_f32_e32 v35, v2, v35
	v_mul_f32_e32 v34, v3, v34
	v_cvt_pk_bf16_f32 v68, v33, v69
	v_cvt_pk_bf16_f32 v69, v70, v71
	v_cvt_pk_bf16_f32 v70, v72, v73
	v_cvt_pk_bf16_f32 v71, v35, v34
	ds_write_b128 v147, v[68:71] offset:27648
	ds_write_b128 v154, v[28:31] offset:57600
	s_or_b64 exec, exec, s[28:29]
	s_and_saveexec_b64 s[28:29], s[8:9]
	s_cbranch_execz .LBB0_189
.LBB0_215:
	v_and_b32_e32 v70, 0xffff0000, v36
	v_lshlrev_b32_e32 v33, 16, v36
	v_mul_f32_e32 v75, v70, v70
	v_lshlrev_b32_e32 v71, 16, v37
	v_fmac_f32_e32 v75, v33, v33
	v_and_b32_e32 v72, 0xffff0000, v37
	v_fmac_f32_e32 v75, v71, v71
	v_lshlrev_b32_e32 v73, 16, v38
	v_fmac_f32_e32 v75, v72, v72
	v_and_b32_e32 v74, 0xffff0000, v38
	v_fmac_f32_e32 v75, v73, v73
	v_and_b32_e32 v34, 0xffff0000, v39
	v_lshlrev_b32_e32 v35, 16, v39
	v_fmac_f32_e32 v75, v74, v74
	v_pk_mul_f32 v[68:69], v[34:35], v[34:35]
	s_nop 0
	v_add_f32_e32 v69, v69, v75
	v_add_f32_e32 v68, v68, v69
	s_nop 1
	v_add_f32_dpp v68, v68, v68 quad_perm:[1,0,3,2] row_mask:0xf bank_mask:0xf
	s_nop 1
	v_add_f32_dpp v68, v68, v68 quad_perm:[2,3,0,1] row_mask:0xf bank_mask:0xf
	s_nop 1
	v_add_f32_dpp v68, v68, v68 row_half_mirror row_mask:0xf bank_mask:0xf
	v_fmamk_f32 v68, v68, 0x3c800000, v204
	v_rsq_f32_e32 v68, v68
	s_nop 0
	v_mul_f32_e32 v69, v68, v70
	v_mul_f32_e32 v70, v68, v71
	v_mul_f32_e32 v71, v68, v72
	v_mul_f32_e32 v33, v68, v33
	v_mul_f32_e32 v72, v68, v73
	v_mul_f32_e32 v69, v5, v69
	v_mul_f32_e32 v70, v6, v70
	v_mul_f32_e32 v71, v7, v71
	v_mul_f32_e32 v73, v68, v74
	v_mul_f32_e32 v35, v68, v35
	v_mul_f32_e32 v34, v68, v34
	v_mul_f32_e32 v33, v4, v33
	v_mul_f32_e32 v72, v0, v72
	v_mul_f32_e32 v73, v1, v73
	v_mul_f32_e32 v35, v2, v35
	v_mul_f32_e32 v34, v3, v34
	v_cvt_pk_bf16_f32 v68, v33, v69
	v_cvt_pk_bf16_f32 v69, v70, v71
	v_cvt_pk_bf16_f32 v70, v72, v73
	v_cvt_pk_bf16_f32 v71, v35, v34
	ds_write_b128 v147, v[68:71] offset:36864
	ds_write_b128 v148, v[40:43] offset:18432
	s_or_b64 exec, exec, s[28:29]
	s_and_saveexec_b64 s[28:29], s[10:11]
	s_cbranch_execz .LBB0_190
.LBB0_216:
	v_and_b32_e32 v70, 0xffff0000, v44
	v_lshlrev_b32_e32 v33, 16, v44
	v_mul_f32_e32 v75, v70, v70
	v_lshlrev_b32_e32 v71, 16, v45
	v_fmac_f32_e32 v75, v33, v33
	v_and_b32_e32 v72, 0xffff0000, v45
	v_fmac_f32_e32 v75, v71, v71
	v_lshlrev_b32_e32 v73, 16, v46
	v_fmac_f32_e32 v75, v72, v72
	v_and_b32_e32 v74, 0xffff0000, v46
	v_fmac_f32_e32 v75, v73, v73
	v_and_b32_e32 v34, 0xffff0000, v47
	v_lshlrev_b32_e32 v35, 16, v47
	v_fmac_f32_e32 v75, v74, v74
	v_pk_mul_f32 v[68:69], v[34:35], v[34:35]
	s_nop 0
	v_add_f32_e32 v69, v69, v75
	v_add_f32_e32 v68, v68, v69
	s_nop 1
	v_add_f32_dpp v68, v68, v68 quad_perm:[1,0,3,2] row_mask:0xf bank_mask:0xf
	s_nop 1
	v_add_f32_dpp v68, v68, v68 quad_perm:[2,3,0,1] row_mask:0xf bank_mask:0xf
	s_nop 1
	v_add_f32_dpp v68, v68, v68 row_half_mirror row_mask:0xf bank_mask:0xf
	v_fmamk_f32 v68, v68, 0x3c800000, v204
	v_rsq_f32_e32 v68, v68
	s_nop 0
	v_mul_f32_e32 v69, v68, v70
	v_mul_f32_e32 v70, v68, v71
	v_mul_f32_e32 v71, v68, v72
	v_mul_f32_e32 v33, v68, v33
	v_mul_f32_e32 v72, v68, v73
	v_mul_f32_e32 v69, v5, v69
	v_mul_f32_e32 v70, v6, v70
	v_mul_f32_e32 v71, v7, v71
	v_mul_f32_e32 v73, v68, v74
	v_mul_f32_e32 v35, v68, v35
	v_mul_f32_e32 v34, v68, v34
	v_mul_f32_e32 v33, v4, v33
	v_mul_f32_e32 v72, v0, v72
	v_mul_f32_e32 v73, v1, v73
	v_mul_f32_e32 v35, v2, v35
	v_mul_f32_e32 v34, v3, v34
	v_cvt_pk_bf16_f32 v68, v33, v69
	v_cvt_pk_bf16_f32 v69, v70, v71
	v_cvt_pk_bf16_f32 v70, v72, v73
	v_cvt_pk_bf16_f32 v71, v35, v34
	ds_write_b128 v147, v[68:71] offset:46080
	ds_write_b128 v148, v[48:51] offset:27648
	s_or_b64 exec, exec, s[28:29]
	s_and_saveexec_b64 s[28:29], s[12:13]
	s_cbranch_execnz .LBB0_191
	s_branch .LBB0_192

; #define LAS __attribute__((address_space(3)))
; __device__ __forceinline__ void unpack8(const u32x4 r, float (&v)[8]) { v[0] = bf_lo(r.x); v[1] = bf_hi(r.x); v[2] = bf_lo(r.y); v[3] = bf_hi(r.y); v[4] = bf_lo(r.z); v[5] = bf_hi(r.z); v[6] = bf_lo(r.w); v[7] = bf_hi(r.w); }
; __device__ __forceinline__ u32x4 pack8(const float (&v)[8]) { u32x4 w; w.x = cvt_pk_bf16(v[0], v[1]); w.y = cvt_pk_bf16(v[2], v[3]); w.z = cvt_pk_bf16(v[4], v[5]); w.w = cvt_pk_bf16(v[6], v[7]); return w; }
; __device__ __forceinline__ void norm_store(LAS bf16_t* dst, const u32x4 raw, const float (&g)[8]) {
;     float v[8]; unpack8(raw, v); float ss = 0.f;
; #pragma unroll
;     for (int t = 0; t < 8; ++t) ss += v[t] * v[t];
;     ss += __shfl_xor(ss, 1); ss += __shfl_xor(ss, 2); ss += __shfl_xor(ss, 4);
;     const float rs = __builtin_amdgcn_rsqf(ss * (1.0f / 64.0f) + EPS);
;     float o[8];
; #pragma unroll
;     for (int t = 0; t < 8; ++t) o[t] = v[t] * rs * g[t];
;     *(LAS u32x4*)dst = pack8(o);
; }
; __device__ __forceinline__ void attn_stage(LAS unsigned char* lds, const AttnPre& P, const float (&gq)[8], const float (&gk)[8], int tid) {
;     ...
;     for (int it = 0; it < 2; ++it) norm_store(Qs + (i0 + 64 * it) * AQP + 8 * c, P.q[it], gq);
.LBB0_242:
	v_and_b32_e32 v70, 0xffff0000, v8
	v_lshlrev_b32_e32 v33, 16, v8
	v_mul_f32_e32 v75, v70, v70
	v_lshlrev_b32_e32 v71, 16, v9
	v_fmac_f32_e32 v75, v33, v33
	v_and_b32_e32 v72, 0xffff0000, v9
	v_fmac_f32_e32 v75, v71, v71
	v_lshlrev_b32_e32 v73, 16, v10
	v_fmac_f32_e32 v75, v72, v72
	v_and_b32_e32 v74, 0xffff0000, v10
	v_fmac_f32_e32 v75, v73, v73
	v_and_b32_e32 v34, 0xffff0000, v11
	v_lshlrev_b32_e32 v35, 16, v11
	v_fmac_f32_e32 v75, v74, v74
	v_pk_mul_f32 v[68:69], v[34:35], v[34:35]
	s_nop 0
	v_add_f32_e32 v69, v69, v75
	v_add_f32_e32 v68, v68, v69
	s_nop 1
	v_add_f32_dpp v68, v68, v68 quad_perm:[1,0,3,2] row_mask:0xf bank_mask:0xf
	s_nop 1
	v_add_f32_dpp v68, v68, v68 quad_perm:[2,3,0,1] row_mask:0xf bank_mask:0xf
	s_nop 1
	v_add_f32_dpp v68, v68, v68 row_half_mirror row_mask:0xf bank_mask:0xf
	v_fmamk_f32 v68, v68, 0x3c800000, v204
	v_rsq_f32_e32 v68, v68
	s_nop 0
	v_mul_f32_e32 v69, v68, v70
	v_mul_f32_e32 v70, v68, v71
	v_mul_f32_e32 v33, v68, v33
	v_mul_f32_e32 v69, v135, v69
	v_mul_f32_e32 v70, v137, v70
	v_mul_f32_e32 v71, v68, v72
	v_mul_f32_e32 v72, v68, v73
	v_mul_f32_e32 v73, v68, v74
	v_mul_f32_e32 v33, v134, v33
	v_mul_f32_e32 v71, v138, v71
	v_mul_f32_e32 v72, v139, v72
	v_mul_f32_e32 v73, v140, v73
	v_mul_f32_e32 v35, v68, v35
	v_mul_f32_e32 v34, v68, v34
	v_cvt_pk_bf16_f32 v68, v33, v69
	v_cvt_pk_bf16_f32 v69, v70, v71
	v_cvt_pk_bf16_f32 v70, v72, v73
	v_mul_f32_e32 v35, v141, v35
	v_mul_f32_e32 v34, v142, v34
	v_cvt_pk_bf16_f32 v71, v35, v34
	ds_write_b128 v146, v[68:71]
	v_and_b32_e32 v70, 0xffff0000, v12
	v_lshlrev_b32_e32 v33, 16, v12
	v_mul_f32_e32 v75, v70, v70
	v_lshlrev_b32_e32 v71, 16, v13
	v_fmac_f32_e32 v75, v33, v33
	v_and_b32_e32 v72, 0xffff0000, v13
	v_fmac_f32_e32 v75, v71, v71
	v_lshlrev_b32_e32 v73, 16, v14
	v_fmac_f32_e32 v75, v72, v72
	v_and_b32_e32 v74, 0xffff0000, v14
	v_fmac_f32_e32 v75, v73, v73
	v_and_b32_e32 v34, 0xffff0000, v15
	v_lshlrev_b32_e32 v35, 16, v15
	v_fmac_f32_e32 v75, v74, v74
	v_pk_mul_f32 v[68:69], v[34:35], v[34:35]
	s_nop 0
	v_add_f32_e32 v69, v69, v75
	v_add_f32_e32 v68, v68, v69
	s_nop 1
	v_add_f32_dpp v68, v68, v68 quad_perm:[1,0,3,2] row_mask:0xf bank_mask:0xf
	s_nop 1
	v_add_f32_dpp v68, v68, v68 quad_perm:[2,3,0,1] row_mask:0xf bank_mask:0xf
	s_nop 1
	v_add_f32_dpp v68, v68, v68 row_half_mirror row_mask:0xf bank_mask:0xf
	v_fmamk_f32 v68, v68, 0x3c800000, v204
	v_rsq_f32_e32 v68, v68
	s_nop 0
	v_mul_f32_e32 v69, v68, v70
	v_mul_f32_e32 v70, v68, v71
	v_mul_f32_e32 v71, v68, v72
	v_mul_f32_e32 v33, v68, v33
	v_mul_f32_e32 v69, v135, v69
	v_mul_f32_e32 v70, v137, v70
	v_mul_f32_e32 v71, v138, v71
	v_mul_f32_e32 v72, v68, v73
	v_mul_f32_e32 v73, v68, v74
	v_mul_f32_e32 v35, v68, v35
	v_mul_f32_e32 v34, v68, v34
	v_mul_f32_e32 v33, v134, v33
	v_mul_f32_e32 v72, v139, v72
	v_mul_f32_e32 v73, v140, v73
	v_mul_f32_e32 v35, v141, v35
	v_mul_f32_e32 v34, v142, v34
	v_cvt_pk_bf16_f32 v68, v33, v69
	v_cvt_pk_bf16_f32 v69, v70, v71
	v_cvt_pk_bf16_f32 v70, v72, v73
	v_cvt_pk_bf16_f32 v71, v35, v34
	ds_write_b128 v146, v[68:71] offset:9216
	s_and_saveexec_b64 s[26:27], s[4:5]
	s_cbranch_execnz .LBB0_271
	s_or_b64 exec, exec, s[26:27]
	s_and_saveexec_b64 s[26:27], s[6:7]
	s_cbranch_execnz .LBB0_272

; #define LAS __attribute__((address_space(3)))
; __device__ __forceinline__ void unpack8(const u32x4 r, float (&v)[8]) { v[0] = bf_lo(r.x); v[1] = bf_hi(r.x); v[2] = bf_lo(r.y); v[3] = bf_hi(r.y); v[4] = bf_lo(r.z); v[5] = bf_hi(r.z); v[6] = bf_lo(r.w); v[7] = bf_hi(r.w); }
; __device__ __forceinline__ u32x4 pack8(const float (&v)[8]) { u32x4 w; w.x = cvt_pk_bf16(v[0], v[1]); w.y = cvt_pk_bf16(v[2], v[3]); w.z = cvt_pk_bf16(v[4], v[5]); w.w = cvt_pk_bf16(v[6], v[7]); return w; }
; __device__ __forceinline__ void norm_store(LAS bf16_t* dst, const u32x4 raw, const float (&g)[8]) {
;     float v[8]; unpack8(raw, v); float ss = 0.f;
; #pragma unroll
;     for (int t = 0; t < 8; ++t) ss += v[t] * v[t];
;     ss += __shfl_xor(ss, 1); ss += __shfl_xor(ss, 2); ss += __shfl_xor(ss, 4);
;     const float rs = __builtin_amdgcn_rsqf(ss * (1.0f / 64.0f) + EPS);
;     float o[8];
; #pragma unroll
;     for (int t = 0; t < 8; ++t) o[t] = v[t] * rs * g[t];
;     *(LAS u32x4*)dst = pack8(o);
; }
; __device__ __forceinline__ void attn_stage(LAS unsigned char* lds, const AttnPre& P, const float (&gq)[8], const float (&gk)[8], int tid) {
;     ...
;     for (int it = 0; it < 5; ++it) { const int i = i0 + 64 * it;
;         if (i < ANR) { norm_store(Ks + i * AQP + 8 * c, P.k[it], gk); *(LAS u32x4*)(Vs + i * AQP + 8 * c) = P.v[it]; } }
.LBB0_247:
	v_and_b32_e32 v70, 0xffff0000, v52
	v_lshlrev_b32_e32 v33, 16, v52
	v_mul_f32_e32 v75, v70, v70
	v_lshlrev_b32_e32 v71, 16, v53
	v_fmac_f32_e32 v75, v33, v33
	v_and_b32_e32 v72, 0xffff0000, v53
	v_fmac_f32_e32 v75, v71, v71
	v_lshlrev_b32_e32 v73, 16, v54
	v_fmac_f32_e32 v75, v72, v72
	v_and_b32_e32 v74, 0xffff0000, v54
	v_fmac_f32_e32 v75, v73, v73
	v_and_b32_e32 v34, 0xffff0000, v55
	v_lshlrev_b32_e32 v35, 16, v55
	v_fmac_f32_e32 v75, v74, v74
	v_pk_mul_f32 v[68:69], v[34:35], v[34:35]
	s_nop 0
	v_add_f32_e32 v69, v69, v75
	v_add_f32_e32 v68, v68, v69
	s_nop 1
	v_add_f32_dpp v68, v68, v68 quad_perm:[1,0,3,2] row_mask:0xf bank_mask:0xf
	s_nop 1
	v_add_f32_dpp v68, v68, v68 quad_perm:[2,3,0,1] row_mask:0xf bank_mask:0xf
	s_nop 1
	v_add_f32_dpp v68, v68, v68 row_half_mirror row_mask:0xf bank_mask:0xf
	v_fmamk_f32 v68, v68, 0x3c800000, v204
	v_rsq_f32_e32 v68, v68
	s_nop 0
	v_mul_f32_e32 v69, v68, v70
	v_mul_f32_e32 v70, v68, v71
	v_mul_f32_e32 v71, v68, v72
	v_mul_f32_e32 v33, v68, v33
	v_mul_f32_e32 v72, v68, v73
	v_mul_f32_e32 v69, v5, v69
	v_mul_f32_e32 v70, v6, v70
	v_mul_f32_e32 v71, v7, v71
	v_mul_f32_e32 v73, v68, v74
	v_mul_f32_e32 v35, v68, v35
	v_mul_f32_e32 v34, v68, v34
	v_mul_f32_e32 v33, v4, v33
	v_mul_f32_e32 v72, v0, v72
	v_mul_f32_e32 v73, v1, v73
	v_mul_f32_e32 v35, v2, v35
	v_mul_f32_e32 v34, v3, v34
	v_cvt_pk_bf16_f32 v68, v33, v69
	v_cvt_pk_bf16_f32 v69, v70, v71
	v_cvt_pk_bf16_f32 v70, v72, v73
	v_cvt_pk_bf16_f32 v71, v35, v34
	ds_write_b128 v146, v[68:71] offset:55296
	ds_write_b128 v147, v[56:59] offset:36864

; #define LAS __attribute__((address_space(3)))
; __device__ __forceinline__ void unpack8(const u32x4 r, float (&v)[8]) { v[0] = bf_lo(r.x); v[1] = bf_hi(r.x); v[2] = bf_lo(r.y); v[3] = bf_hi(r.y); v[4] = bf_lo(r.z); v[5] = bf_hi(r.z); v[6] = bf_lo(r.w); v[7] = bf_hi(r.w); }
; __device__ __forceinline__ u32x4 pack8(const float (&v)[8]) { u32x4 w; w.x = cvt_pk_bf16(v[0], v[1]); w.y = cvt_pk_bf16(v[2], v[3]); w.z = cvt_pk_bf16(v[4], v[5]); w.w = cvt_pk_bf16(v[6], v[7]); return w; }
; __device__ __forceinline__ void norm_store(LAS bf16_t* dst, const u32x4 raw, const float (&g)[8]) {
;     float v[8]; unpack8(raw, v); float ss = 0.f;
; #pragma unroll
;     for (int t = 0; t < 8; ++t) ss += v[t] * v[t];
;     ss += __shfl_xor(ss, 1); ss += __shfl_xor(ss, 2); ss += __shfl_xor(ss, 4);
;     const float rs = __builtin_amdgcn_rsqf(ss * (1.0f / 64.0f) + EPS);
;     float o[8];
; #pragma unroll
;     for (int t = 0; t < 8; ++t) o[t] = v[t] * rs * g[t];
;     *(LAS u32x4*)dst = pack8(o);
; }
; __device__ __forceinline__ void attn_stage(LAS unsigned char* lds, const AttnPre& P, const float (&gq)[8], const float (&gk)[8], int tid) {
;     ...
; #pragma unroll
;     for (int it = 0; it < 5; ++it) { const int i = i0 + 64 * it;
;         if (i < ANR) { norm_store(Ks + i * AQP + 8 * c, P.k[it], gk); *(LAS u32x4*)(Vs + i * AQP + 8 * c) = P.v[it]; } }
.LBB0_271:
	v_and_b32_e32 v70, 0xffff0000, v20
	v_lshlrev_b32_e32 v33, 16, v20
	v_mul_f32_e32 v75, v70, v70
	v_lshlrev_b32_e32 v71, 16, v21
	v_fmac_f32_e32 v75, v33, v33
	v_and_b32_e32 v72, 0xffff0000, v21
	v_fmac_f32_e32 v75, v71, v71
	v_lshlrev_b32_e32 v73, 16, v22
	v_fmac_f32_e32 v75, v72, v72
	v_and_b32_e32 v74, 0xffff0000, v22
	v_fmac_f32_e32 v75, v73, v73
	v_and_b32_e32 v34, 0xffff0000, v23
	v_lshlrev_b32_e32 v35, 16, v23
	v_fmac_f32_e32 v75, v74, v74
	v_pk_mul_f32 v[68:69], v[34:35], v[34:35]
	s_nop 0
	v_add_f32_e32 v69, v69, v75
	v_add_f32_e32 v68, v68, v69
	s_nop 1
	v_add_f32_dpp v68, v68, v68 quad_perm:[1,0,3,2] row_mask:0xf bank_mask:0xf
	s_nop 1
	v_add_f32_dpp v68, v68, v68 quad_perm:[2,3,0,1] row_mask:0xf bank_mask:0xf
	s_nop 1
	v_add_f32_dpp v68, v68, v68 row_half_mirror row_mask:0xf bank_mask:0xf
	v_fmamk_f32 v68, v68, 0x3c800000, v204
	v_rsq_f32_e32 v68, v68
	s_nop 0
	v_mul_f32_e32 v69, v68, v70
	v_mul_f32_e32 v70, v68, v71
	v_mul_f32_e32 v71, v68, v72
	v_mul_f32_e32 v33, v68, v33
	v_mul_f32_e32 v72, v68, v73
	v_mul_f32_e32 v69, v5, v69
	v_mul_f32_e32 v70, v6, v70
	v_mul_f32_e32 v71, v7, v71
	v_mul_f32_e32 v73, v68, v74
	v_mul_f32_e32 v35, v68, v35
	v_mul_f32_e32 v34, v68, v34
	v_mul_f32_e32 v33, v4, v33
	v_mul_f32_e32 v72, v0, v72
	v_mul_f32_e32 v73, v1, v73
	v_mul_f32_e32 v35, v2, v35
	v_mul_f32_e32 v34, v3, v34
	v_cvt_pk_bf16_f32 v68, v33, v69
	v_cvt_pk_bf16_f32 v69, v70, v71
	v_cvt_pk_bf16_f32 v70, v72, v73
	v_cvt_pk_bf16_f32 v71, v35, v34
	ds_write_b128 v146, v[68:71] offset:18432
	ds_write_b128 v146, v[24:27] offset:57600
	s_or_b64 exec, exec, s[26:27]
	s_and_saveexec_b64 s[26:27], s[6:7]
	s_cbranch_execz .LBB0_244
.LBB0_272:
	v_and_b32_e32 v70, 0xffff0000, v28
	v_lshlrev_b32_e32 v33, 16, v28
	v_mul_f32_e32 v75, v70, v70
	v_lshlrev_b32_e32 v71, 16, v29
	v_fmac_f32_e32 v75, v33, v33
	v_and_b32_e32 v72, 0xffff0000, v29
	v_fmac_f32_e32 v75, v71, v71
	v_lshlrev_b32_e32 v73, 16, v30
	v_fmac_f32_e32 v75, v72, v72
	v_and_b32_e32 v74, 0xffff0000, v30
	v_fmac_f32_e32 v75, v73, v73
	v_and_b32_e32 v34, 0xffff0000, v31
	v_lshlrev_b32_e32 v35, 16, v31
	v_fmac_f32_e32 v75, v74, v74
	v_pk_mul_f32 v[68:69], v[34:35], v[34:35]
	s_nop 0
	v_add_f32_e32 v69, v69, v75
	v_add_f32_e32 v68, v68, v69
	s_nop 1
	v_add_f32_dpp v68, v68, v68 quad_perm:[1,0,3,2] row_mask:0xf bank_mask:0xf
	s_nop 1
	v_add_f32_dpp v68, v68, v68 quad_perm:[2,3,0,1] row_mask:0xf bank_mask:0xf
	s_nop 1
	v_add_f32_dpp v68, v68, v68 row_half_mirror row_mask:0xf bank_mask:0xf
	v_fmamk_f32 v68, v68, 0x3c800000, v204
	v_rsq_f32_e32 v68, v68
	s_nop 0
	v_mul_f32_e32 v69, v68, v70
	v_mul_f32_e32 v70, v68, v71
	v_mul_f32_e32 v71, v68, v72
	v_mul_f32_e32 v33, v68, v33
	v_mul_f32_e32 v72, v68, v73
	v_mul_f32_e32 v69, v5, v69
	v_mul_f32_e32 v70, v6, v70
	v_mul_f32_e32 v71, v7, v71
	v_mul_f32_e32 v73, v68, v74
	v_mul_f32_e32 v35, v68, v35
	v_mul_f32_e32 v34, v68, v34
	v_mul_f32_e32 v33, v4, v33
	v_mul_f32_e32 v72, v0, v72
	v_mul_f32_e32 v73, v1, v73
	v_mul_f32_e32 v35, v2, v35
	v_mul_f32_e32 v34, v3, v34
	v_cvt_pk_bf16_f32 v68, v33, v69
	v_cvt_pk_bf16_f32 v69, v70, v71
	v_cvt_pk_bf16_f32 v70, v72, v73
	v_cvt_pk_bf16_f32 v71, v35, v34
	ds_write_b128 v146, v[68:71] offset:27648
	ds_write_b128 v153, v[16:19] offset:57600
	s_or_b64 exec, exec, s[26:27]
	s_and_saveexec_b64 s[26:27], s[8:9]
	s_cbranch_execz .LBB0_245
.LBB0_273:
	v_and_b32_e32 v70, 0xffff0000, v36
	v_lshlrev_b32_e32 v33, 16, v36
	v_mul_f32_e32 v75, v70, v70
	v_lshlrev_b32_e32 v71, 16, v37
	v_fmac_f32_e32 v75, v33, v33
	v_and_b32_e32 v72, 0xffff0000, v37
	v_fmac_f32_e32 v75, v71, v71
	v_lshlrev_b32_e32 v73, 16, v38
	v_fmac_f32_e32 v75, v72, v72
	v_and_b32_e32 v74, 0xffff0000, v38
	v_fmac_f32_e32 v75, v73, v73
	v_and_b32_e32 v34, 0xffff0000, v39
	v_lshlrev_b32_e32 v35, 16, v39
	v_fmac_f32_e32 v75, v74, v74
	v_pk_mul_f32 v[68:69], v[34:35], v[34:35]
	s_nop 0
	v_add_f32_e32 v69, v69, v75
	v_add_f32_e32 v68, v68, v69
	s_nop 1
	v_add_f32_dpp v68, v68, v68 quad_perm:[1,0,3,2] row_mask:0xf bank_mask:0xf
	s_nop 1
	v_add_f32_dpp v68, v68, v68 quad_perm:[2,3,0,1] row_mask:0xf bank_mask:0xf
	s_nop 1
	v_add_f32_dpp v68, v68, v68 row_half_mirror row_mask:0xf bank_mask:0xf
	v_fmamk_f32 v68, v68, 0x3c800000, v204
	v_rsq_f32_e32 v68, v68
	s_nop 0
	v_mul_f32_e32 v69, v68, v70
	v_mul_f32_e32 v70, v68, v71
	v_mul_f32_e32 v71, v68, v72
	v_mul_f32_e32 v33, v68, v33
	v_mul_f32_e32 v72, v68, v73
	v_mul_f32_e32 v69, v5, v69
	v_mul_f32_e32 v70, v6, v70
	v_mul_f32_e32 v71, v7, v71
	v_mul_f32_e32 v73, v68, v74
	v_mul_f32_e32 v35, v68, v35
	v_mul_f32_e32 v34, v68, v34
	v_mul_f32_e32 v33, v4, v33
	v_mul_f32_e32 v72, v0, v72
	v_mul_f32_e32 v73, v1, v73
	v_mul_f32_e32 v35, v2, v35
	v_mul_f32_e32 v34, v3, v34
	v_cvt_pk_bf16_f32 v68, v33, v69
	v_cvt_pk_bf16_f32 v69, v70, v71
	v_cvt_pk_bf16_f32 v70, v72, v73
	v_cvt_pk_bf16_f32 v71, v35, v34
	ds_write_b128 v146, v[68:71] offset:36864
	ds_write_b128 v147, v[40:43] offset:18432
	s_or_b64 exec, exec, s[26:27]
	s_and_saveexec_b64 s[26:27], s[10:11]
	s_cbranch_execz .LBB0_246
.LBB0_274:
	v_and_b32_e32 v70, 0xffff0000, v44
	v_lshlrev_b32_e32 v33, 16, v44
	v_mul_f32_e32 v75, v70, v70
	v_lshlrev_b32_e32 v71, 16, v45
	v_fmac_f32_e32 v75, v33, v33
	v_and_b32_e32 v72, 0xffff0000, v45
	v_fmac_f32_e32 v75, v71, v71
	v_lshlrev_b32_e32 v73, 16, v46
	v_fmac_f32_e32 v75, v72, v72
	v_and_b32_e32 v74, 0xffff0000, v46
	v_fmac_f32_e32 v75, v73, v73
	v_and_b32_e32 v34, 0xffff0000, v47
	v_lshlrev_b32_e32 v35, 16, v47
	v_fmac_f32_e32 v75, v74, v74
	v_pk_mul_f32 v[68:69], v[34:35], v[34:35]
	s_nop 0
	v_add_f32_e32 v69, v69, v75
	v_add_f32_e32 v68, v68, v69
	s_nop 1
	v_add_f32_dpp v68, v68, v68 quad_perm:[1,0,3,2] row_mask:0xf bank_mask:0xf
	s_nop 1
	v_add_f32_dpp v68, v68, v68 quad_perm:[2,3,0,1] row_mask:0xf bank_mask:0xf
	s_nop 1
	v_add_f32_dpp v68, v68, v68 row_half_mirror row_mask:0xf bank_mask:0xf
	v_fmamk_f32 v68, v68, 0x3c800000, v204
	v_rsq_f32_e32 v68, v68
	s_nop 0
	v_mul_f32_e32 v69, v68, v70
	v_mul_f32_e32 v70, v68, v71
	v_mul_f32_e32 v71, v68, v72
	v_mul_f32_e32 v33, v68, v33
	v_mul_f32_e32 v72, v68, v73
	v_mul_f32_e32 v69, v5, v69
	v_mul_f32_e32 v70, v6, v70
	v_mul_f32_e32 v71, v7, v71
	v_mul_f32_e32 v73, v68, v74
	v_mul_f32_e32 v35, v68, v35
	v_mul_f32_e32 v34, v68, v34
	v_mul_f32_e32 v33, v4, v33
	v_mul_f32_e32 v72, v0, v72
	v_mul_f32_e32 v73, v1, v73
	v_mul_f32_e32 v35, v2, v35
	v_mul_f32_e32 v34, v3, v34
	v_cvt_pk_bf16_f32 v68, v33, v69
	v_cvt_pk_bf16_f32 v69, v70, v71
	v_cvt_pk_bf16_f32 v70, v72, v73
	v_cvt_pk_bf16_f32 v71, v35, v34
	ds_write_b128 v146, v[68:71] offset:46080
	ds_write_b128 v147, v[48:51] offset:27648
	s_or_b64 exec, exec, s[26:27]
	s_and_saveexec_b64 s[26:27], s[12:13]
	s_cbranch_execnz .LBB0_247
	s_branch .LBB0_248
